# v2 + local barrier: first poll of the arrival counter issued together with the arrival atomic (one round trip less for near-last arrivers)
# baseline (speedup 1.0000x reference)
; __device__ __forceinline__ int hw_lane() { int l; asm volatile("v_mbcnt_lo_u32_b32 %0, -1, 0\n\tv_mbcnt_hi_u32_b32 %0, -1, %0" : "=v"(l)); return l; }
; __device__ __forceinline__ unsigned xb_ld(unsigned* p)              { return __hip_atomic_load(p, __ATOMIC_RELAXED, __HIP_MEMORY_SCOPE_AGENT); }
; __device__ __forceinline__ unsigned xb_add(unsigned* p, unsigned v) { return __hip_atomic_fetch_add(p, v, __ATOMIC_RELAXED, __HIP_MEMORY_SCOPE_AGENT); }
; #define XB_SPIN(cond, bar) do { unsigned _sp = 0; while (cond) { __builtin_amdgcn_s_sleep(1); \
;     if ((++_sp & 255u) == 0u) { if (xb_ld(&(bar)[XB_TMO])) break; if (_sp > XB_SPIN_CAP) { atomicAdd(&(bar)[XB_TMO], 1u); break; } } } } while (0)
; __device__ __forceinline__ void xcd_barrier_local(const XcdBarrier& b) {
;     ...
;     if (b.wave == 0 && hw_lane() == 0) {
;         unsigned* bar = b.bar;
;         __builtin_amdgcn_s_waitcnt(0);
;         const unsigned nloc = b.st[0] ? b.st[0] : 1u;
;         const unsigned old = xb_add(&bar[XB_XSUB(b.x)], 1u);
;         const unsigned target = (old / nloc + 1u) * nloc;
;         if (old + 1u == target) (void)xb_add(&bar[XB_XGEN(b.x)], 1u);
;         else XB_SPIN(xb_ld(&bar[XB_XSUB(b.x)]) < target, bar);
.LBB0_859:
	s_or_b64 exec, exec, s[14:15]
	global_load_dword v3, v201, s[8:9] sc1
	buffer_inv sc1
	s_waitcnt vmcnt(0)
	v_readfirstlane_b32 s4, v2
	v_readfirstlane_b32 s100, v3
	s_waitcnt lgkmcnt(0)
	v_cvt_f32_u32_e32 v2, v0
	v_sub_u32_e32 v3, 0, v0
	v_add_u32_e32 v1, s4, v1
	s_mov_b64 s[16:17], 0
	v_rcp_iflag_f32_e32 v2, v2
	s_nop 0
	v_mul_f32_e32 v2, 0x4f7ffffe, v2
	v_cvt_u32_f32_e32 v2, v2
	v_mul_lo_u32 v3, v3, v2
	v_mul_hi_u32 v3, v2, v3
	v_add_u32_e32 v2, v2, v3
	v_mul_hi_u32 v2, v1, v2
	v_mul_lo_u32 v3, v2, v0
	v_sub_u32_e32 v3, v1, v3
	v_cmp_ge_u32_e32 vcc, v3, v0
	v_add_u32_e32 v4, 1, v2
	v_add_u32_e32 v1, 1, v1
	v_cndmask_b32_e32 v2, v2, v4, vcc
	v_sub_u32_e32 v4, v3, v0
	v_cndmask_b32_e32 v3, v3, v4, vcc
	v_cmp_ge_u32_e32 vcc, v3, v0
	v_add_u32_e32 v3, 1, v2
	s_nop 0
	v_cndmask_b32_e32 v2, v2, v3, vcc
	v_mul_lo_u32 v2, v0, v2
	v_add_u32_e32 v0, v2, v0
	v_cmp_ne_u32_e32 vcc, v1, v0
	s_and_saveexec_b64 s[4:5], vcc
	s_xor_b64 s[12:13], exec, s[4:5]
	s_cbranch_execz .LBB0_869
	v_mov_b32_e32 v1, s100
	s_mov_b64 s[18:19], 0
	s_waitcnt vmcnt(0)
	v_cmp_lt_u32_e32 vcc, v1, v0
	s_and_saveexec_b64 s[16:17], vcc
	s_cbranch_execz .LBB0_872
	s_add_u32 s14, s2, 0x200
	s_addc_u32 s15, s3, 0
	s_mov_b32 s4, 1
	s_branch .LBB0_863

; __device__ __forceinline__ int hw_lane() { int l; asm volatile("v_mbcnt_lo_u32_b32 %0, -1, 0\n\tv_mbcnt_hi_u32_b32 %0, -1, %0" : "=v"(l)); return l; }
; __device__ __forceinline__ unsigned xb_ld(unsigned* p)              { return __hip_atomic_load(p, __ATOMIC_RELAXED, __HIP_MEMORY_SCOPE_AGENT); }
; __device__ __forceinline__ unsigned xb_add(unsigned* p, unsigned v) { return __hip_atomic_fetch_add(p, v, __ATOMIC_RELAXED, __HIP_MEMORY_SCOPE_AGENT); }
; #define XB_SPIN(cond, bar) do { unsigned _sp = 0; while (cond) { __builtin_amdgcn_s_sleep(1); \
;     if ((++_sp & 255u) == 0u) { if (xb_ld(&(bar)[XB_TMO])) break; if (_sp > XB_SPIN_CAP) { atomicAdd(&(bar)[XB_TMO], 1u); break; } } } } while (0)
; __device__ __forceinline__ void xcd_barrier_local(const XcdBarrier& b) {
;     ...
;     if (b.wave == 0 && hw_lane() == 0) {
;         unsigned* bar = b.bar;
;         __builtin_amdgcn_s_waitcnt(0);
;         const unsigned nloc = b.st[0] ? b.st[0] : 1u;
;         const unsigned old = xb_add(&bar[XB_XSUB(b.x)], 1u);
;         const unsigned target = (old / nloc + 1u) * nloc;
;         if (old + 1u == target) (void)xb_add(&bar[XB_XGEN(b.x)], 1u);
;         else XB_SPIN(xb_ld(&bar[XB_XSUB(b.x)]) < target, bar);
.LBB0_956:
	s_or_b64 exec, exec, s[14:15]
	global_load_dword v3, v201, s[10:11] sc1
	buffer_inv sc1
	s_waitcnt vmcnt(0)
	v_readfirstlane_b32 s1, v2
	v_readfirstlane_b32 s100, v3
	s_waitcnt lgkmcnt(0)
	v_cvt_f32_u32_e32 v2, v0
	v_sub_u32_e32 v3, 0, v0
	v_add_u32_e32 v1, s1, v1
	s_mov_b64 s[16:17], 0
	v_rcp_iflag_f32_e32 v2, v2
	s_nop 0
	v_mul_f32_e32 v2, 0x4f7ffffe, v2
	v_cvt_u32_f32_e32 v2, v2
	v_mul_lo_u32 v3, v3, v2
	v_mul_hi_u32 v3, v2, v3
	v_add_u32_e32 v2, v2, v3
	v_mul_hi_u32 v2, v1, v2
	v_mul_lo_u32 v3, v2, v0
	v_sub_u32_e32 v3, v1, v3
	v_cmp_ge_u32_e32 vcc, v3, v0
	v_add_u32_e32 v4, 1, v2
	v_add_u32_e32 v1, 1, v1
	v_cndmask_b32_e32 v2, v2, v4, vcc
	v_sub_u32_e32 v4, v3, v0
	v_cndmask_b32_e32 v3, v3, v4, vcc
	v_cmp_ge_u32_e32 vcc, v3, v0
	v_add_u32_e32 v3, 1, v2
	s_nop 0
	v_cndmask_b32_e32 v2, v2, v3, vcc
	v_mul_lo_u32 v2, v0, v2
	v_add_u32_e32 v0, v2, v0
	v_cmp_ne_u32_e32 vcc, v1, v0
	s_and_saveexec_b64 s[4:5], vcc
	s_xor_b64 s[12:13], exec, s[4:5]
	s_cbranch_execz .LBB0_966
	v_mov_b32_e32 v1, s100
	s_mov_b64 s[18:19], 0
	s_waitcnt vmcnt(0)
	v_cmp_lt_u32_e32 vcc, v1, v0
	s_and_saveexec_b64 s[16:17], vcc
	s_cbranch_execz .LBB0_969
	s_add_u32 s14, s2, 0x200
	s_addc_u32 s15, s3, 0
	s_mov_b32 s1, 1
	s_branch .LBB0_960

; __device__ __forceinline__ int hw_lane() { int l; asm volatile("v_mbcnt_lo_u32_b32 %0, -1, 0\n\tv_mbcnt_hi_u32_b32 %0, -1, %0" : "=v"(l)); return l; }
; __device__ __forceinline__ unsigned xb_ld(unsigned* p)              { return __hip_atomic_load(p, __ATOMIC_RELAXED, __HIP_MEMORY_SCOPE_AGENT); }
; __device__ __forceinline__ unsigned xb_add(unsigned* p, unsigned v) { return __hip_atomic_fetch_add(p, v, __ATOMIC_RELAXED, __HIP_MEMORY_SCOPE_AGENT); }
; #define XB_SPIN(cond, bar) do { unsigned _sp = 0; while (cond) { __builtin_amdgcn_s_sleep(1); \
;     if ((++_sp & 255u) == 0u) { if (xb_ld(&(bar)[XB_TMO])) break; if (_sp > XB_SPIN_CAP) { atomicAdd(&(bar)[XB_TMO], 1u); break; } } } } while (0)
; __device__ __forceinline__ void xcd_barrier_local(const XcdBarrier& b) {
;     ...
;     if (b.wave == 0 && hw_lane() == 0) {
;         unsigned* bar = b.bar;
;         __builtin_amdgcn_s_waitcnt(0);
;         const unsigned nloc = b.st[0] ? b.st[0] : 1u;
;         const unsigned old = xb_add(&bar[XB_XSUB(b.x)], 1u);
;         const unsigned target = (old / nloc + 1u) * nloc;
;         if (old + 1u == target) (void)xb_add(&bar[XB_XGEN(b.x)], 1u);
;         else XB_SPIN(xb_ld(&bar[XB_XSUB(b.x)]) < target, bar);
.LBB0_1294:
	s_or_b64 exec, exec, s[10:11]
	global_load_dword v3, v201, s[6:7] sc1
	buffer_inv sc1
	s_waitcnt vmcnt(0)
	v_readfirstlane_b32 s8, v2
	v_readfirstlane_b32 s100, v3
	s_waitcnt lgkmcnt(0)
	v_cvt_f32_u32_e32 v2, v0
	v_sub_u32_e32 v3, 0, v0
	v_add_u32_e32 v1, s8, v1
	s_mov_b64 s[12:13], 0
	v_rcp_iflag_f32_e32 v2, v2
	s_nop 0
	v_mul_f32_e32 v2, 0x4f7ffffe, v2
	v_cvt_u32_f32_e32 v2, v2
	v_mul_lo_u32 v3, v3, v2
	v_mul_hi_u32 v3, v2, v3
	v_add_u32_e32 v2, v2, v3
	v_mul_hi_u32 v2, v1, v2
	v_mul_lo_u32 v3, v2, v0
	v_sub_u32_e32 v3, v1, v3
	v_cmp_ge_u32_e32 vcc, v3, v0
	v_add_u32_e32 v4, 1, v2
	v_add_u32_e32 v1, 1, v1
	v_cndmask_b32_e32 v2, v2, v4, vcc
	v_sub_u32_e32 v4, v3, v0
	v_cndmask_b32_e32 v3, v3, v4, vcc
	v_cmp_ge_u32_e32 vcc, v3, v0
	v_add_u32_e32 v3, 1, v2
	s_nop 0
	v_cndmask_b32_e32 v2, v2, v3, vcc
	v_mul_lo_u32 v2, v0, v2
	v_add_u32_e32 v0, v2, v0
	v_cmp_ne_u32_e32 vcc, v1, v0
	s_and_saveexec_b64 s[8:9], vcc
	s_xor_b64 s[8:9], exec, s[8:9]
	s_cbranch_execz .LBB0_1304
	v_mov_b32_e32 v1, s100
	s_mov_b64 s[14:15], 0
	s_waitcnt vmcnt(0)
	v_cmp_lt_u32_e32 vcc, v1, v0
	s_and_saveexec_b64 s[12:13], vcc
	s_cbranch_execz .LBB0_1307
	s_add_u32 s10, s0, 0x200
	s_addc_u32 s11, s1, 0
	s_mov_b32 s25, 1
	s_branch .LBB0_1298

; __device__ __forceinline__ int hw_lane() { int l; asm volatile("v_mbcnt_lo_u32_b32 %0, -1, 0\n\tv_mbcnt_hi_u32_b32 %0, -1, %0" : "=v"(l)); return l; }
; __device__ __forceinline__ unsigned xb_ld(unsigned* p)              { return __hip_atomic_load(p, __ATOMIC_RELAXED, __HIP_MEMORY_SCOPE_AGENT); }
; __device__ __forceinline__ unsigned xb_add(unsigned* p, unsigned v) { return __hip_atomic_fetch_add(p, v, __ATOMIC_RELAXED, __HIP_MEMORY_SCOPE_AGENT); }
; #define XB_SPIN(cond, bar) do { unsigned _sp = 0; while (cond) { __builtin_amdgcn_s_sleep(1); \
;     if ((++_sp & 255u) == 0u) { if (xb_ld(&(bar)[XB_TMO])) break; if (_sp > XB_SPIN_CAP) { atomicAdd(&(bar)[XB_TMO], 1u); break; } } } } while (0)
; __device__ __forceinline__ void xcd_barrier_local(const XcdBarrier& b) {
;     ...
;     if (b.wave == 0 && hw_lane() == 0) {
;         unsigned* bar = b.bar;
;         __builtin_amdgcn_s_waitcnt(0);
;         const unsigned nloc = b.st[0] ? b.st[0] : 1u;
;         const unsigned old = xb_add(&bar[XB_XSUB(b.x)], 1u);
;         const unsigned target = (old / nloc + 1u) * nloc;
;         if (old + 1u == target) (void)xb_add(&bar[XB_XGEN(b.x)], 1u);
;         else XB_SPIN(xb_ld(&bar[XB_XSUB(b.x)]) < target, bar);
.LBB0_1675:
	s_or_b64 exec, exec, s[8:9]
	global_load_dword v3, v201, s[4:5] sc1
	buffer_inv sc1
	s_waitcnt vmcnt(0)
	v_readfirstlane_b32 s6, v2
	v_readfirstlane_b32 s100, v3
	s_waitcnt lgkmcnt(0)
	v_cvt_f32_u32_e32 v2, v0
	v_sub_u32_e32 v3, 0, v0
	v_add_u32_e32 v1, s6, v1
	s_mov_b64 s[10:11], 0
	v_rcp_iflag_f32_e32 v2, v2
	s_nop 0
	v_mul_f32_e32 v2, 0x4f7ffffe, v2
	v_cvt_u32_f32_e32 v2, v2
	v_mul_lo_u32 v3, v3, v2
	v_mul_hi_u32 v3, v2, v3
	v_add_u32_e32 v2, v2, v3
	v_mul_hi_u32 v2, v1, v2
	v_mul_lo_u32 v3, v2, v0
	v_sub_u32_e32 v3, v1, v3
	v_cmp_ge_u32_e32 vcc, v3, v0
	v_add_u32_e32 v4, 1, v2
	v_add_u32_e32 v1, 1, v1
	v_cndmask_b32_e32 v2, v2, v4, vcc
	v_sub_u32_e32 v4, v3, v0
	v_cndmask_b32_e32 v3, v3, v4, vcc
	v_cmp_ge_u32_e32 vcc, v3, v0
	v_add_u32_e32 v3, 1, v2
	s_nop 0
	v_cndmask_b32_e32 v2, v2, v3, vcc
	v_mul_lo_u32 v2, v0, v2
	v_add_u32_e32 v0, v2, v0
	v_cmp_ne_u32_e32 vcc, v1, v0
	s_and_saveexec_b64 s[6:7], vcc
	s_xor_b64 s[6:7], exec, s[6:7]
	s_cbranch_execz .LBB0_1685
	v_mov_b32_e32 v1, s100
	s_mov_b64 s[12:13], 0
	s_waitcnt vmcnt(0)
	v_cmp_lt_u32_e32 vcc, v1, v0
	s_and_saveexec_b64 s[10:11], vcc
	s_cbranch_execz .LBB0_1688
	s_add_u32 s8, s0, 0x200
	s_addc_u32 s9, s1, 0
	s_mov_b32 s23, 1
	s_branch .LBB0_1679

; __device__ __forceinline__ int hw_lane() { int l; asm volatile("v_mbcnt_lo_u32_b32 %0, -1, 0\n\tv_mbcnt_hi_u32_b32 %0, -1, %0" : "=v"(l)); return l; }
; __device__ __forceinline__ unsigned xb_ld(unsigned* p)              { return __hip_atomic_load(p, __ATOMIC_RELAXED, __HIP_MEMORY_SCOPE_AGENT); }
; __device__ __forceinline__ unsigned xb_add(unsigned* p, unsigned v) { return __hip_atomic_fetch_add(p, v, __ATOMIC_RELAXED, __HIP_MEMORY_SCOPE_AGENT); }
; #define XB_SPIN(cond, bar) do { unsigned _sp = 0; while (cond) { __builtin_amdgcn_s_sleep(1); \
;     if ((++_sp & 255u) == 0u) { if (xb_ld(&(bar)[XB_TMO])) break; if (_sp > XB_SPIN_CAP) { atomicAdd(&(bar)[XB_TMO], 1u); break; } } } } while (0)
; __device__ __forceinline__ void xcd_barrier_local(const XcdBarrier& b) {
;     ...
;     if (b.wave == 0 && hw_lane() == 0) {
;         unsigned* bar = b.bar;
;         __builtin_amdgcn_s_waitcnt(0);
;         const unsigned nloc = b.st[0] ? b.st[0] : 1u;
;         const unsigned old = xb_add(&bar[XB_XSUB(b.x)], 1u);
;         const unsigned target = (old / nloc + 1u) * nloc;
;         if (old + 1u == target) (void)xb_add(&bar[XB_XGEN(b.x)], 1u);
;         else XB_SPIN(xb_ld(&bar[XB_XSUB(b.x)]) < target, bar);
.LBB0_1815:
	s_or_b64 exec, exec, s[12:13]
	global_load_dword v3, v201, s[6:7] sc1
	buffer_inv sc1
	s_waitcnt vmcnt(0)
	v_readfirstlane_b32 s10, v2
	v_readfirstlane_b32 s100, v3
	s_waitcnt lgkmcnt(0)
	v_cvt_f32_u32_e32 v2, v0
	v_sub_u32_e32 v3, 0, v0
	v_add_u32_e32 v1, s10, v1
	s_mov_b64 s[14:15], 0
	v_rcp_iflag_f32_e32 v2, v2
	s_nop 0
	v_mul_f32_e32 v2, 0x4f7ffffe, v2
	v_cvt_u32_f32_e32 v2, v2
	v_mul_lo_u32 v3, v3, v2
	v_mul_hi_u32 v3, v2, v3
	v_add_u32_e32 v2, v2, v3
	v_mul_hi_u32 v2, v1, v2
	v_mul_lo_u32 v3, v2, v0
	v_sub_u32_e32 v3, v1, v3
	v_cmp_ge_u32_e32 vcc, v3, v0
	v_add_u32_e32 v4, 1, v2
	v_add_u32_e32 v1, 1, v1
	v_cndmask_b32_e32 v2, v2, v4, vcc
	v_sub_u32_e32 v4, v3, v0
	v_cndmask_b32_e32 v3, v3, v4, vcc
	v_cmp_ge_u32_e32 vcc, v3, v0
	v_add_u32_e32 v3, 1, v2
	s_nop 0
	v_cndmask_b32_e32 v2, v2, v3, vcc
	v_mul_lo_u32 v2, v0, v2
	v_add_u32_e32 v0, v2, v0
	v_cmp_ne_u32_e32 vcc, v1, v0
	s_and_saveexec_b64 s[10:11], vcc
	s_xor_b64 s[10:11], exec, s[10:11]
	s_cbranch_execz .LBB0_1825
	v_mov_b32_e32 v1, s100
	s_mov_b64 s[16:17], 0
	s_waitcnt vmcnt(0)
	v_cmp_lt_u32_e32 vcc, v1, v0
	s_and_saveexec_b64 s[14:15], vcc
	s_cbranch_execz .LBB0_1828
	s_add_u32 s12, s0, 0x200
	s_addc_u32 s13, s1, 0
	s_mov_b32 s27, 1
	s_branch .LBB0_1819

; __device__ __forceinline__ int hw_lane() { int l; asm volatile("v_mbcnt_lo_u32_b32 %0, -1, 0\n\tv_mbcnt_hi_u32_b32 %0, -1, %0" : "=v"(l)); return l; }
; __device__ __forceinline__ unsigned xb_ld(unsigned* p)              { return __hip_atomic_load(p, __ATOMIC_RELAXED, __HIP_MEMORY_SCOPE_AGENT); }
; __device__ __forceinline__ unsigned xb_add(unsigned* p, unsigned v) { return __hip_atomic_fetch_add(p, v, __ATOMIC_RELAXED, __HIP_MEMORY_SCOPE_AGENT); }
; #define XB_SPIN(cond, bar) do { unsigned _sp = 0; while (cond) { __builtin_amdgcn_s_sleep(1); \
;     if ((++_sp & 255u) == 0u) { if (xb_ld(&(bar)[XB_TMO])) break; if (_sp > XB_SPIN_CAP) { atomicAdd(&(bar)[XB_TMO], 1u); break; } } } } while (0)
; __device__ __forceinline__ void xcd_barrier_local(const XcdBarrier& b) {
;     ...
;     if (b.wave == 0 && hw_lane() == 0) {
;         unsigned* bar = b.bar;
;         __builtin_amdgcn_s_waitcnt(0);
;         const unsigned nloc = b.st[0] ? b.st[0] : 1u;
;         const unsigned old = xb_add(&bar[XB_XSUB(b.x)], 1u);
;         const unsigned target = (old / nloc + 1u) * nloc;
;         if (old + 1u == target) (void)xb_add(&bar[XB_XGEN(b.x)], 1u);
;         else XB_SPIN(xb_ld(&bar[XB_XSUB(b.x)]) < target, bar);
.LBB0_2335:
	s_or_b64 exec, exec, s[12:13]
	global_load_dword v3, v201, s[4:5] sc1
	buffer_inv sc1
	s_waitcnt vmcnt(0)
	v_readfirstlane_b32 s10, v2
	v_readfirstlane_b32 s100, v3
	s_waitcnt lgkmcnt(0)
	v_cvt_f32_u32_e32 v2, v0
	v_sub_u32_e32 v3, 0, v0
	v_add_u32_e32 v1, s10, v1
	s_mov_b64 s[14:15], 0
	v_rcp_iflag_f32_e32 v2, v2
	s_nop 0
	v_mul_f32_e32 v2, 0x4f7ffffe, v2
	v_cvt_u32_f32_e32 v2, v2
	v_mul_lo_u32 v3, v3, v2
	v_mul_hi_u32 v3, v2, v3
	v_add_u32_e32 v2, v2, v3
	v_mul_hi_u32 v2, v1, v2
	v_mul_lo_u32 v3, v2, v0
	v_sub_u32_e32 v3, v1, v3
	v_cmp_ge_u32_e32 vcc, v3, v0
	v_add_u32_e32 v4, 1, v2
	v_add_u32_e32 v1, 1, v1
	v_cndmask_b32_e32 v2, v2, v4, vcc
	v_sub_u32_e32 v4, v3, v0
	v_cndmask_b32_e32 v3, v3, v4, vcc
	v_cmp_ge_u32_e32 vcc, v3, v0
	v_add_u32_e32 v3, 1, v2
	s_nop 0
	v_cndmask_b32_e32 v2, v2, v3, vcc
	v_mul_lo_u32 v2, v0, v2
	v_add_u32_e32 v0, v2, v0
	v_cmp_ne_u32_e32 vcc, v1, v0
	s_and_saveexec_b64 s[10:11], vcc
	s_xor_b64 s[10:11], exec, s[10:11]
	s_cbranch_execz .LBB0_2345
	v_mov_b32_e32 v1, s100
	s_mov_b64 s[16:17], 0
	s_waitcnt vmcnt(0)
	v_cmp_lt_u32_e32 vcc, v1, v0
	s_and_saveexec_b64 s[14:15], vcc
	s_cbranch_execz .LBB0_2348
	s_add_u32 s12, s0, 0x200
	s_addc_u32 s13, s1, 0
	s_mov_b32 s27, 1
	s_branch .LBB0_2339

; __global__ void __launch_bounds__(NWAVES * 64, 2) fwd(Args args) {
	.amdhsa_kernel _Z3fwd4Args
		.amdhsa_group_segment_fixed_size 0
		.amdhsa_private_segment_fixed_size 0
		.amdhsa_kernarg_size 480
		.amdhsa_user_sgpr_count 2
		.amdhsa_user_sgpr_dispatch_ptr 0
		.amdhsa_user_sgpr_queue_ptr 0
		.amdhsa_user_sgpr_kernarg_segment_ptr 1
		.amdhsa_user_sgpr_dispatch_id 0
		.amdhsa_user_sgpr_kernarg_preload_length 0
		.amdhsa_user_sgpr_kernarg_preload_offset 0
		.amdhsa_user_sgpr_private_segment_size 0
		.amdhsa_uses_dynamic_stack 0
		.amdhsa_enable_private_segment 0
		.amdhsa_system_sgpr_workgroup_id_x 1
		.amdhsa_system_sgpr_workgroup_id_y 0
		.amdhsa_system_sgpr_workgroup_id_z 0
		.amdhsa_system_sgpr_workgroup_info 0
		.amdhsa_system_vgpr_workitem_id 0
		.amdhsa_next_free_vgpr 256
		.amdhsa_next_free_sgpr 102
		.amdhsa_accum_offset 256
		.amdhsa_reserve_vcc 1
		.amdhsa_float_round_mode_32 0
		.amdhsa_float_round_mode_16_64 0
		.amdhsa_float_denorm_mode_32 3
		.amdhsa_float_denorm_mode_16_64 3
		.amdhsa_dx10_clamp 1
		.amdhsa_ieee_mode 1
		.amdhsa_fp16_overflow 0
		.amdhsa_tg_split 0
		.amdhsa_exception_fp_ieee_invalid_op 0
		.amdhsa_exception_fp_denorm_src 0
		.amdhsa_exception_fp_ieee_div_zero 0
		.amdhsa_exception_fp_ieee_overflow 0
		.amdhsa_exception_fp_ieee_underflow 0
		.amdhsa_exception_fp_ieee_inexact 0
		.amdhsa_exception_int_div_zero 0
	.end_amdhsa_kernel

; __global__ void __launch_bounds__(NWAVES * 64, 2) fwd(Args args) {
amdhsa.kernels:
  - .agpr_count:     0
    .args:
      - .offset:         0
        .size:           224
        .value_kind:     by_value
      - .offset:         224
        .size:           4
        .value_kind:     hidden_block_count_x
      - .offset:         228
        .size:           4
        .value_kind:     hidden_block_count_y
      - .offset:         232
        .size:           4
        .value_kind:     hidden_block_count_z
      - .offset:         236
        .size:           2
        .value_kind:     hidden_group_size_x
      - .offset:         238
        .size:           2
        .value_kind:     hidden_group_size_y
      - .offset:         240
        .size:           2
        .value_kind:     hidden_group_size_z
      - .offset:         242
        .size:           2
        .value_kind:     hidden_remainder_x
      - .offset:         244
        .size:           2
        .value_kind:     hidden_remainder_y
      - .offset:         246
        .size:           2
        .value_kind:     hidden_remainder_z
      - .offset:         264
        .size:           8
        .value_kind:     hidden_global_offset_x
      - .offset:         272
        .size:           8
        .value_kind:     hidden_global_offset_y
      - .offset:         280
        .size:           8
        .value_kind:     hidden_global_offset_z
      - .offset:         288
        .size:           2
        .value_kind:     hidden_grid_dims
      - .offset:         344
        .size:           4
        .value_kind:     hidden_dynamic_lds_size
    .group_segment_fixed_size: 0
    .kernarg_segment_align: 8
    .kernarg_segment_size: 480
    .language:       OpenCL C
    .language_version:
      - 2
      - 0
    .max_flat_workgroup_size: 512
    .name:           _Z3fwd4Args
    .private_segment_fixed_size: 0
    .sgpr_count:     108
    .sgpr_spill_count: 141
    .symbol:         _Z3fwd4Args.kd
    .uniform_work_group_size: 1
    .uses_dynamic_stack: false
    .vgpr_count:     256
    .vgpr_spill_count: 0
    .wavefront_size: 64
